# v25 minus 9 dead t==0 selects in the scan loader loop, conversion gs scaling with 8 packed multiplies instead of 16 scalar ones
# speedup vs baseline: 1.0141x; 1.0020x over previous
.Lcis_a_done:
	v_lshlrev_b32_e32 v156, 16, v104
	v_and_b32_e32 v104, 0xffff0000, v104
	v_lshlrev_b32_e32 v178, 16, v105
	v_and_b32_e32 v105, 0xffff0000, v105
	v_lshlrev_b32_e32 v179, 16, v106
	v_and_b32_e32 v106, 0xffff0000, v106
	v_lshlrev_b32_e32 v180, 16, v107
	v_and_b32_e32 v107, 0xffff0000, v107
	v_cmp_eq_u32_e64 s[48:49], s20, v136
	v_lshlrev_b32_e32 v162, 16, v100
	v_and_b32_e32 v163, 0xffff0000, v100
	v_lshlrev_b32_e32 v176, 16, v101
	v_and_b32_e32 v177, 0xffff0000, v101
	v_lshlrev_b32_e32 v100, 16, v102
	v_and_b32_e32 v101, 0xffff0000, v102
	v_lshlrev_b32_e32 v102, 16, v103
	v_and_b32_e32 v103, 0xffff0000, v103
	v_cndmask_b32_e64 v181, v107, 0, s[48:49]
	v_cndmask_b32_e64 v182, v179, 0, s[48:49]
	v_cndmask_b32_e64 v179, v106, 0, s[48:49]
	v_cndmask_b32_e64 v106, v178, 0, s[48:49]
	v_cndmask_b32_e64 v107, v105, 0, s[48:49]
	v_sub_f32_e32 v105, v104, v163
	v_sub_f32_e32 v104, v156, v162
	v_sub_f32_e32 v107, v107, v177
	v_sub_f32_e32 v106, v106, v176
	v_sub_f32_e32 v179, v179, v101
	v_sub_f32_e32 v178, v182, v100
	v_sub_f32_e32 v181, v181, v103
	v_sub_f32_e32 v180, v180, v102
	v_pk_fma_f32 v[102:103], v[38:39], v[180:181], v[102:103]
	v_pk_fma_f32 v[100:101], v[36:37], v[178:179], v[100:101]
	v_pk_fma_f32 v[106:107], v[34:35], v[106:107], v[176:177]
	s_and_b64 vcc, exec, s[44:45]
	v_pk_fma_f32 v[104:105], v[32:33], v[104:105], v[162:163]
	s_cbranch_vccnz .LBB0_210
	v_lshlrev_b32_e32 v156, 16, v92
	v_and_b32_e32 v92, 0xffff0000, v92
	v_lshlrev_b32_e32 v162, 16, v93
	v_and_b32_e32 v163, 0xffff0000, v93
	v_lshlrev_b32_e32 v176, 16, v94
	v_and_b32_e32 v177, 0xffff0000, v94
	v_lshlrev_b32_e32 v178, 16, v95
	v_and_b32_e32 v179, 0xffff0000, v95
	v_sub_f32_e32 v93, v92, v105
	v_sub_f32_e32 v92, v156, v104
	v_sub_f32_e32 v95, v163, v107
	v_sub_f32_e32 v94, v162, v106
	v_sub_f32_e32 v163, v177, v101
	v_sub_f32_e32 v162, v176, v100
	v_sub_f32_e32 v177, v179, v103
	v_sub_f32_e32 v176, v178, v102
	v_lshlrev_b32_e32 v178, 16, v88
	v_and_b32_e32 v179, 0xffff0000, v88
	v_lshlrev_b32_e32 v88, 16, v89
	v_and_b32_e32 v89, 0xffff0000, v89
	v_lshlrev_b32_e32 v180, 16, v90
	v_and_b32_e32 v181, 0xffff0000, v90
	v_lshlrev_b32_e32 v90, 16, v91
	v_and_b32_e32 v91, 0xffff0000, v91
	v_pk_fma_f32 v[102:103], v[176:177], v[90:91], v[102:103]
	v_pk_fma_f32 v[100:101], v[162:163], v[180:181], v[100:101]
	v_pk_fma_f32 v[106:107], v[94:95], v[88:89], v[106:107]
	v_pk_fma_f32 v[104:105], v[92:93], v[178:179], v[104:105]
.LBB0_210:
	v_lshlrev_b32_e32 v163, 16, v62
	v_and_b32_e32 v62, 0xffff0000, v62
	v_lshlrev_b32_e32 v176, 16, v63
	v_and_b32_e32 v63, 0xffff0000, v63
	v_lshlrev_b32_e32 v177, 16, v56
	v_and_b32_e32 v56, 0xffff0000, v56
	v_lshlrev_b32_e32 v178, 16, v57
	v_and_b32_e32 v57, 0xffff0000, v57
	v_lshlrev_b32_e32 v179, 16, v58
	v_and_b32_e32 v58, 0xffff0000, v58
	v_lshlrev_b32_e32 v180, 16, v59
	v_and_b32_e32 v59, 0xffff0000, v59
	v_lshlrev_b32_e32 v90, 16, v70
	v_and_b32_e32 v91, 0xffff0000, v70
	v_lshlrev_b32_e32 v70, 16, v71
	v_and_b32_e32 v71, 0xffff0000, v71
	v_cndmask_b32_e64 v181, v57, 0, s[48:49]
	v_cndmask_b32_e64 v182, v59, 0, s[48:49]
	v_cndmask_b32_e64 v183, v56, 0, s[48:49]
	v_cndmask_b32_e64 v184, v58, 0, s[48:49]
	v_cndmask_b32_e64 v58, v176, 0, s[48:49]
	v_cndmask_b32_e64 v59, v63, 0, s[48:49]
	v_cndmask_b32_e64 v56, v163, 0, s[48:49]
	v_cndmask_b32_e64 v57, v62, 0, s[48:49]
	v_lshlrev_b32_e32 v92, 16, v64
	v_and_b32_e32 v93, 0xffff0000, v64
	v_lshlrev_b32_e32 v94, 16, v66
	v_and_b32_e32 v95, 0xffff0000, v66
	v_sub_f32_e32 v57, v57, v91
	v_sub_f32_e32 v56, v56, v90
	v_sub_f32_e32 v59, v59, v71
	v_sub_f32_e32 v58, v58, v70
	v_lshlrev_b32_e32 v64, 16, v65
	v_and_b32_e32 v65, 0xffff0000, v65
	v_lshlrev_b32_e32 v66, 16, v67
	v_and_b32_e32 v67, 0xffff0000, v67
	v_lshlrev_b32_e32 v162, 16, v61
	v_pk_fma_f32 v[58:59], v[30:31], v[58:59], v[70:71]
	v_pk_fma_f32 v[56:57], v[28:29], v[56:57], v[90:91]
	v_sub_f32_e32 v71, v184, v95
	v_sub_f32_e32 v70, v179, v94
	v_sub_f32_e32 v91, v183, v93
	v_sub_f32_e32 v90, v177, v92
	v_cndmask_b32_e64 v62, v162, 0, s[48:49]
	v_sub_f32_e32 v163, v182, v67
	v_sub_f32_e32 v162, v180, v66
	v_sub_f32_e32 v177, v181, v65
	v_sub_f32_e32 v176, v178, v64
	v_pk_fma_f32 v[92:93], v[24:25], v[90:91], v[92:93]
	v_pk_fma_f32 v[90:91], v[20:21], v[70:71], v[94:95]
	v_pk_fma_f32 v[176:177], v[26:27], v[176:177], v[64:65]
	v_pk_fma_f32 v[162:163], v[22:23], v[162:163], v[66:67]
	v_pk_mul_f32 v[70:71], v[16:17], v[90:91]
	v_pk_mul_f32 v[94:95], v[12:13], v[92:93]
	v_pk_mul_f32 v[178:179], v[18:19], v[162:163]
	v_pk_mul_f32 v[180:181], v[14:15], v[176:177]
	v_pk_mul_f32 v[182:183], v[94:95], v[94:95]
	v_pk_mul_f32 v[184:185], v[70:71], v[70:71]
	v_pk_mul_f32 v[64:65], v[180:181], v[180:181]
	v_pk_mul_f32 v[66:67], v[178:179], v[178:179]
	v_mov_b32_e32 v186, v182
	v_mov_b32_e32 v187, v184
	v_mov_b32_e32 v184, v183
	v_pk_add_f32 v[182:183], v[186:187], v[184:185]
	v_mov_b32_e32 v184, v64
	v_mov_b32_e32 v185, v66
	v_mov_b32_e32 v66, v65
	v_pk_add_f32 v[64:65], v[184:185], v[66:67]
	v_and_b32_e32 v61, 0xffff0000, v61
	v_pk_add_f32 v[64:65], v[182:183], v[64:65]
	v_lshlrev_b32_e32 v88, 16, v68
	v_add_f32_e32 v64, v64, v65
	ds_bpermute_b32 v65, v165, v64
	v_and_b32_e32 v89, 0xffff0000, v68
	v_lshlrev_b32_e32 v68, 16, v69
	v_and_b32_e32 v69, 0xffff0000, v69
	v_lshlrev_b32_e32 v156, 16, v60
	v_and_b32_e32 v60, 0xffff0000, v60
	v_cndmask_b32_e64 v63, v61, 0, s[48:49]
	v_sub_f32_e32 v63, v63, v69
	v_sub_f32_e32 v62, v62, v68
	v_sub_f32_e32 v61, v60, v89
	v_sub_f32_e32 v60, v156, v88
	v_pk_fma_f32 v[62:63], v[10:11], v[62:63], v[68:69]
	v_lshlrev_b32_e32 v69, 16, v44
	v_and_b32_e32 v156, 0xffff0000, v44
	s_waitcnt lgkmcnt(0)
	v_add_f32_e32 v44, v64, v65
	ds_bpermute_b32 v64, v166, v44
	v_lshlrev_b32_e32 v192, 16, v45
	v_and_b32_e32 v193, 0xffff0000, v45
	v_lshlrev_b32_e32 v194, 16, v46
	v_and_b32_e32 v195, 0xffff0000, v46
	s_waitcnt lgkmcnt(0)
	v_add_f32_e32 v44, v44, v64
	ds_bpermute_b32 v45, v167, v44
	v_lshlrev_b32_e32 v202, 16, v47
	v_and_b32_e32 v203, 0xffff0000, v47
	v_lshlrev_b32_e32 v46, 16, v40
	v_and_b32_e32 v47, 0xffff0000, v40
	s_waitcnt lgkmcnt(0)
	v_add_f32_e32 v40, v44, v45
	v_mul_f32_e32 v44, 0x4f800000, v40
	v_cmp_gt_f32_e32 vcc, s76, v40
	v_lshlrev_b32_e32 v184, 16, v42
	v_and_b32_e32 v185, 0xffff0000, v42
	v_cndmask_b32_e32 v44, v40, v44, vcc
	v_sqrt_f32_e32 v45, v44
	v_lshlrev_b32_e32 v182, 16, v43
	v_and_b32_e32 v183, 0xffff0000, v43
	v_lshlrev_b32_e32 v40, 16, v41
	v_add_u32_e32 v64, -1, v45
	v_fma_f32 v65, -v64, v45, v44
	v_cmp_ge_f32_e64 s[48:49], 0, v65
	v_add_u32_e32 v65, 1, v45
	v_and_b32_e32 v41, 0xffff0000, v41
	v_cndmask_b32_e64 v64, v45, v64, s[48:49]
	v_fma_f32 v45, -v65, v45, v44
	v_cmp_lt_f32_e64 s[48:49], 0, v45
	s_bitcmp1_b32 s19, 0
	v_pk_add_f32 v[66:67], v[46:47], -1.0 op_sel_hi:[1,0]
	v_cndmask_b32_e64 v45, v64, v65, s[48:49]
	v_mul_f32_e32 v64, 0x37800000, v45
	v_cndmask_b32_e32 v45, v45, v64, vcc
	v_cmp_class_f32_e32 vcc, v44, v196
	v_pk_fma_f32 v[60:61], v[8:9], v[60:61], v[88:89]
	v_pk_fma_f32 v[88:89], v[4:5], v[66:67], 1.0 op_sel_hi:[1,1,0]
	v_cndmask_b32_e32 v44, v45, v44, vcc
	v_max_f32_e32 v44, 0x2b8cbccc, v44
	v_div_scale_f32 v45, s[22:23], v44, v44, 1.0
	v_rcp_f32_e32 v64, v45
	s_cselect_b32 s22, 0xa800, 0
	v_mul_f32_e32 v66, 0x3fb8aa3b, v202
	v_mul_f32_e32 v67, 0x3fb8aa3b, v203
	v_fma_f32 v42, -v45, v64, 1.0
	v_fmac_f32_e32 v64, v42, v64
	v_div_scale_f32 v42, vcc, 1.0, v44, 1.0
	v_mul_f32_e32 v43, v42, v64
	v_fma_f32 v65, -v45, v43, v42
	v_fmac_f32_e32 v43, v65, v64
	v_fma_f32 v42, -v45, v43, v42
	v_div_fmas_f32 v42, v42, v64, v43
	v_div_fixup_f32 v68, v42, v44, 1.0
	v_pk_add_f32 v[42:43], v[182:183], -1.0 op_sel_hi:[1,0]
	v_pk_add_f32 v[44:45], v[184:185], -1.0 op_sel_hi:[1,0]
	v_pk_add_f32 v[64:65], v[40:41], -1.0 op_sel_hi:[1,0]
	v_pk_fma_f32 v[188:189], v[0:1], v[44:45], 1.0 op_sel_hi:[1,1,0]
	v_pk_fma_f32 v[186:187], v[6:7], v[64:65], 1.0 op_sel_hi:[1,1,0]
	v_pk_fma_f32 v[190:191], v[2:3], v[42:43], 1.0 op_sel_hi:[1,1,0]
	v_mul_f32_e32 v42, 0x3fb8aa3b, v69
	v_mul_f32_e32 v43, 0x3fb8aa3b, v156
	v_mul_f32_e32 v44, 0x3fb8aa3b, v192
	v_mul_f32_e32 v45, 0x3fb8aa3b, v193
	v_mul_f32_e32 v64, 0x3fb8aa3b, v194
	v_mul_f32_e32 v65, 0x3fb8aa3b, v195
	v_pk_mul_f32 v[194:195], v[180:181], v[68:69] op_sel_hi:[1,0]
	v_exp_f32_e32 v42, v42
	v_exp_f32_e32 v43, v43
	v_exp_f32_e32 v44, v44
	v_exp_f32_e32 v45, v45
	v_pk_mul_f32 v[192:193], v[94:95], v[68:69] op_sel_hi:[1,0]
	v_pk_mul_f32 v[180:181], v[70:71], v[68:69] op_sel_hi:[1,0]
	v_pk_mul_f32 v[202:203], v[178:179], v[68:69] op_sel_hi:[1,0]
	v_pk_mul_f32 v[68:69], v[188:189], v[90:91]
	v_pk_mul_f32 v[90:91], v[186:187], v[176:177]
	v_pk_mul_f32 v[186:187], v[194:195], v[40:41]
	v_add_u32_e32 v40, s22, v168
	v_exp_f32_e32 v64, v64
	v_exp_f32_e32 v65, v65
	v_exp_f32_e32 v66, v66
	v_exp_f32_e32 v67, v67
	v_add_u32_e32 v41, v40, v169
	v_pk_mul_f32 v[70:71], v[190:191], v[162:163]
	v_pk_mul_f32 v[88:89], v[88:89], v[92:93]
	v_xor_b32_e32 v95, 0x80000000, v203
	v_xor_b32_e32 v94, 0x80000000, v202
	v_xor_b32_e32 v93, 0x80000000, v181
	v_xor_b32_e32 v92, 0x80000000, v180
	v_xor_b32_e32 v179, 0x80000000, v195
	v_xor_b32_e32 v178, 0x80000000, v194
	v_xor_b32_e32 v177, 0x80000000, v193
	v_xor_b32_e32 v176, 0x80000000, v192
	v_pk_mul_f32 v[182:183], v[202:203], v[182:183]
	v_pk_mul_f32 v[180:181], v[180:181], v[184:185]
	v_pk_mul_f32 v[184:185], v[192:193], v[46:47]
	ds_write_b128 v41, v[60:63]
	ds_write_b128 v41, v[56:59] offset:16
	ds_write_b128 v41, v[42:45] offset:256
	ds_write_b128 v41, v[64:67] offset:272
	ds_write_b128 v41, v[88:91] offset:512
	ds_write_b128 v41, v[68:71] offset:528
	ds_write_b128 v41, v[176:179] offset:768
	ds_write_b128 v41, v[92:95] offset:784
	ds_write_b128 v41, v[184:187] offset:1024
	ds_write_b128 v41, v[180:183] offset:1040
	s_and_saveexec_b64 s[22:23], s[46:47]
	s_cbranch_execz .LBB0_212
	v_add_u32_e32 v40, v40, v170
	ds_write_b128 v40, v[104:107] offset:1280
	ds_write_b128 v40, v[100:103] offset:1296
.LBB0_212:
	s_or_b64 exec, exec, s[22:23]
	s_and_b32 s22, s24, 0x800
	s_addk_i32 s24, 0x800
	v_add_u32_e32 v40, s22, v171
	s_add_u32 s20, s20, 32
	ds_read_b64 v[40:41], v40
	s_addc_u32 s21, s21, 0
	s_mov_b64 s[22:23], 0x48000
	s_add_i32 s19, s19, 1
	s_waitcnt lgkmcnt(0)
	v_cvt_pk_bf16_f32 v42, v40, v41
	v_lshl_add_u64 v[40:41], s[14:15], 0, v[148:149]
	v_lshl_add_u64 v[148:149], v[148:149], 0, s[92:93]
	v_lshl_add_u64 v[150:151], v[150:151], 0, s[92:93]
	v_lshl_add_u64 v[154:155], v[154:155], 0, s[22:23]
	s_cmp_eq_u32 s53, 1
	s_cbranch_scc0 .Lcis_b_done
	s_waitcnt vmcnt(0)
	s_cmp_eq_u32 s61, 2
	s_cbranch_scc1 .Lcis_b_flat
	s_cmp_eq_u32 s61, 0
	s_cbranch_scc1 .Lcis_b_nogs
	v_pk_mul_f32 v[232:233], v[232:233], v[248:249] op_sel_hi:[1,0]
	v_pk_mul_f32 v[234:235], v[234:235], v[248:249] op_sel_hi:[1,0]
	v_pk_mul_f32 v[236:237], v[236:237], v[248:249] op_sel:[0,1] op_sel_hi:[1,1]
	v_pk_mul_f32 v[238:239], v[238:239], v[248:249] op_sel:[0,1] op_sel_hi:[1,1]
	v_pk_mul_f32 v[240:241], v[240:241], v[250:251] op_sel_hi:[1,0]
	v_pk_mul_f32 v[242:243], v[242:243], v[250:251] op_sel_hi:[1,0]
	v_pk_mul_f32 v[244:245], v[244:245], v[250:251] op_sel:[0,1] op_sel_hi:[1,1]
	v_pk_mul_f32 v[246:247], v[246:247], v[250:251] op_sel:[0,1] op_sel_hi:[1,1]
